# lever 2 de-serialisation: per-layer T5-bias LUT build unrolled, all nine relative-bias loads issued before one wait
# baseline (speedup 1.0000x reference)
; __device__ __forceinline__ void nsa_unit(const Params& p, int bg, int jq, LAS unsigned char* lds, int wave, int lane, bool build_lut) {
;     ...
;     if (build_lut) {
;         for (int e = lane; e < 4 * 129; e += 64) {
;             const int rr = e / 129, n = e % 129;
;             int bk = n;
;             if (n >= 16) bk = 16 + (n >= 19) + (n >= 21) + (n >= 24) + (n >= 27) + (n >= 31) + (n >= 35) + (n >= 40) + (n >= 46) + (n >= 52) + (n >= 59) + (n >= 67) + (n >= 77) + (n >= 87) + (n >= 99) + (n >= 113);
;             lut[rr * 132 + n] = relb[bk * 8 + g * 4 + rr] * LOG2E;
;         }
;     }
.LBB0_1046:
	v_mov_b32_e32 v1, v222
	s_movk_i32 s6, 0xa8
	v_readfirstlane_b32 s4, v1
	s_ashr_i32 s12, s4, 6
	v_mov_b32_e32 v1, v222
	s_cmp_eq_u32 s27, 0
	s_waitcnt vmcnt(8)
	v_and_b32_e32 v145, 63, v1
	s_cselect_b64 s[4:5], -1, 0
	s_ashr_i32 s7, s6, 31
	s_add_u32 s6, s0, s6
	s_addc_u32 s7, s1, s7
	s_load_dwordx2 s[14:15], s[6:7], 0x0
	s_movk_i32 s7, 0x204
	v_cmp_gt_i32_e32 vcc, s7, v145
	s_mov_b32 s6, 8
	s_mul_i32 s18, s12, 0x4c00
	s_and_b64 s[8:9], s[4:5], vcc
	s_and_saveexec_b64 s[4:5], s[8:9]
	s_cbranch_execz .LBB0_1051
	s_ashr_i32 s7, s6, 31
	s_add_u32 s6, s0, s6
	s_addc_u32 s7, s1, s7
	s_load_dwordx2 s[6:7], s[6:7], 0x0
	s_add_i32 s8, s18, 0
	s_addk_i32 s8, 0x2100
	v_lshl_add_u32 v2, v145, 2, s8
	v_mov_b32_e32 v4, v145
	v_mul_hi_i32 v1, v4, s2
	v_lshrrev_b32_e32 v3, 31, v1
	v_ashrrev_i32_e32 v1, 3, v1
	v_add_u32_e32 v1, v1, v3
	v_mul_u32_u24_e32 v3, 0x81, v1
	v_sub_u32_e32 v6, v4, v3
	v_mul_u32_u24_e32 v3, 12, v1
	v_add_u32_e32 v241, v2, v3
	v_mov_b32_e32 v5, 16
	v_sub_u32_e32 v7, 18, v6
	v_sub_u32_e32 v3, 20, v6
	v_lshrrev_b32_e32 v7, 31, v7
	v_lshrrev_b32_e32 v3, 31, v3
	v_add3_u32 v5, v5, v7, v3
	v_sub_u32_e32 v7, 23, v6
	v_sub_u32_e32 v3, 26, v6
	v_lshrrev_b32_e32 v7, 31, v7
	v_lshrrev_b32_e32 v3, 31, v3
	v_add3_u32 v5, v5, v7, v3
	v_sub_u32_e32 v7, 30, v6
	v_sub_u32_e32 v3, 34, v6
	v_lshrrev_b32_e32 v7, 31, v7
	v_lshrrev_b32_e32 v3, 31, v3
	v_add3_u32 v5, v5, v7, v3
	v_sub_u32_e32 v7, 39, v6
	v_sub_u32_e32 v3, 45, v6
	v_lshrrev_b32_e32 v7, 31, v7
	v_lshrrev_b32_e32 v3, 31, v3
	v_add3_u32 v5, v5, v7, v3
	v_sub_u32_e32 v7, 51, v6
	v_sub_u32_e32 v3, 58, v6
	v_lshrrev_b32_e32 v7, 31, v7
	v_lshrrev_b32_e32 v3, 31, v3
	v_add3_u32 v5, v5, v7, v3
	v_sub_u32_e32 v7, 66, v6
	v_sub_u32_e32 v3, 76, v6
	v_lshrrev_b32_e32 v7, 31, v7
	v_lshrrev_b32_e32 v3, 31, v3
	v_add3_u32 v5, v5, v7, v3
	v_sub_u32_e32 v7, 86, v6
	v_sub_u32_e32 v3, 98, v6
	v_lshrrev_b32_e32 v7, 31, v7
	v_lshrrev_b32_e32 v3, 31, v3
	v_add3_u32 v5, v5, v7, v3
	v_sub_u32_e32 v7, 112, v6
	v_lshrrev_b32_e32 v7, 31, v7
	v_add_u32_e32 v5, v5, v7
	v_min_u32_e32 v5, v5, v6
	v_lshlrev_b32_e32 v3, 3, v5
	v_add3_u32 v232, v1, s3, v3
	v_lshlrev_b32_e32 v232, 2, v232
	v_add_u32_e32 v4, 64, v145
	v_mul_hi_i32 v1, v4, s2
	v_lshrrev_b32_e32 v3, 31, v1
	v_ashrrev_i32_e32 v1, 3, v1
	v_add_u32_e32 v1, v1, v3
	v_mul_u32_u24_e32 v3, 0x81, v1
	v_sub_u32_e32 v6, v4, v3
	v_mul_u32_u24_e32 v3, 12, v1
	v_add_u32_e32 v242, v2, v3
	v_mov_b32_e32 v5, 16
	v_sub_u32_e32 v7, 18, v6
	v_sub_u32_e32 v3, 20, v6
	v_lshrrev_b32_e32 v7, 31, v7
	v_lshrrev_b32_e32 v3, 31, v3
	v_add3_u32 v5, v5, v7, v3
	v_sub_u32_e32 v7, 23, v6
	v_sub_u32_e32 v3, 26, v6
	v_lshrrev_b32_e32 v7, 31, v7
	v_lshrrev_b32_e32 v3, 31, v3
	v_add3_u32 v5, v5, v7, v3
	v_sub_u32_e32 v7, 30, v6
	v_sub_u32_e32 v3, 34, v6
	v_lshrrev_b32_e32 v7, 31, v7
	v_lshrrev_b32_e32 v3, 31, v3
	v_add3_u32 v5, v5, v7, v3
	v_sub_u32_e32 v7, 39, v6
	v_sub_u32_e32 v3, 45, v6
	v_lshrrev_b32_e32 v7, 31, v7
	v_lshrrev_b32_e32 v3, 31, v3
	v_add3_u32 v5, v5, v7, v3
	v_sub_u32_e32 v7, 51, v6
	v_sub_u32_e32 v3, 58, v6
	v_lshrrev_b32_e32 v7, 31, v7
	v_lshrrev_b32_e32 v3, 31, v3
	v_add3_u32 v5, v5, v7, v3
	v_sub_u32_e32 v7, 66, v6
	v_sub_u32_e32 v3, 76, v6
	v_lshrrev_b32_e32 v7, 31, v7
	v_lshrrev_b32_e32 v3, 31, v3
	v_add3_u32 v5, v5, v7, v3
	v_sub_u32_e32 v7, 86, v6
	v_sub_u32_e32 v3, 98, v6
	v_lshrrev_b32_e32 v7, 31, v7
	v_lshrrev_b32_e32 v3, 31, v3
	v_add3_u32 v5, v5, v7, v3
	v_sub_u32_e32 v7, 112, v6
	v_lshrrev_b32_e32 v7, 31, v7
	v_add_u32_e32 v5, v5, v7
	v_min_u32_e32 v5, v5, v6
	v_lshlrev_b32_e32 v3, 3, v5
	v_add3_u32 v233, v1, s3, v3
	v_lshlrev_b32_e32 v233, 2, v233
	v_add_u32_e32 v4, 128, v145
	v_mul_hi_i32 v1, v4, s2
	v_lshrrev_b32_e32 v3, 31, v1
	v_ashrrev_i32_e32 v1, 3, v1
	v_add_u32_e32 v1, v1, v3
	v_mul_u32_u24_e32 v3, 0x81, v1
	v_sub_u32_e32 v6, v4, v3
	v_mul_u32_u24_e32 v3, 12, v1
	v_add_u32_e32 v243, v2, v3
	v_mov_b32_e32 v5, 16
	v_sub_u32_e32 v7, 18, v6
	v_sub_u32_e32 v3, 20, v6
	v_lshrrev_b32_e32 v7, 31, v7
	v_lshrrev_b32_e32 v3, 31, v3
	v_add3_u32 v5, v5, v7, v3
	v_sub_u32_e32 v7, 23, v6
	v_sub_u32_e32 v3, 26, v6
	v_lshrrev_b32_e32 v7, 31, v7
	v_lshrrev_b32_e32 v3, 31, v3
	v_add3_u32 v5, v5, v7, v3
	v_sub_u32_e32 v7, 30, v6
	v_sub_u32_e32 v3, 34, v6
	v_lshrrev_b32_e32 v7, 31, v7
	v_lshrrev_b32_e32 v3, 31, v3
	v_add3_u32 v5, v5, v7, v3
	v_sub_u32_e32 v7, 39, v6
	v_sub_u32_e32 v3, 45, v6
	v_lshrrev_b32_e32 v7, 31, v7
	v_lshrrev_b32_e32 v3, 31, v3
	v_add3_u32 v5, v5, v7, v3
	v_sub_u32_e32 v7, 51, v6
	v_sub_u32_e32 v3, 58, v6
	v_lshrrev_b32_e32 v7, 31, v7
	v_lshrrev_b32_e32 v3, 31, v3
	v_add3_u32 v5, v5, v7, v3
	v_sub_u32_e32 v7, 66, v6
	v_sub_u32_e32 v3, 76, v6
	v_lshrrev_b32_e32 v7, 31, v7
	v_lshrrev_b32_e32 v3, 31, v3
	v_add3_u32 v5, v5, v7, v3
	v_sub_u32_e32 v7, 86, v6
	v_sub_u32_e32 v3, 98, v6
	v_lshrrev_b32_e32 v7, 31, v7
	v_lshrrev_b32_e32 v3, 31, v3
	v_add3_u32 v5, v5, v7, v3
	v_sub_u32_e32 v7, 112, v6
	v_lshrrev_b32_e32 v7, 31, v7
	v_add_u32_e32 v5, v5, v7
	v_min_u32_e32 v5, v5, v6
	v_lshlrev_b32_e32 v3, 3, v5
	v_add3_u32 v234, v1, s3, v3
	v_lshlrev_b32_e32 v234, 2, v234
	v_add_u32_e32 v4, 192, v145
	v_mul_hi_i32 v1, v4, s2
	v_lshrrev_b32_e32 v3, 31, v1
	v_ashrrev_i32_e32 v1, 3, v1
	v_add_u32_e32 v1, v1, v3
	v_mul_u32_u24_e32 v3, 0x81, v1
	v_sub_u32_e32 v6, v4, v3
	v_mul_u32_u24_e32 v3, 12, v1
	v_add_u32_e32 v244, v2, v3
	v_mov_b32_e32 v5, 16
	v_sub_u32_e32 v7, 18, v6
	v_sub_u32_e32 v3, 20, v6
	v_lshrrev_b32_e32 v7, 31, v7
	v_lshrrev_b32_e32 v3, 31, v3
	v_add3_u32 v5, v5, v7, v3
	v_sub_u32_e32 v7, 23, v6
	v_sub_u32_e32 v3, 26, v6
	v_lshrrev_b32_e32 v7, 31, v7
	v_lshrrev_b32_e32 v3, 31, v3
	v_add3_u32 v5, v5, v7, v3
	v_sub_u32_e32 v7, 30, v6
; __device__ __forceinline__ void nsa_unit(const Params& p, int bg, int jq, LAS unsigned char* lds, int wave, int lane, bool build_lut) {
;     ...
;     if (build_lut) {
;         for (int e = lane; e < 4 * 129; e += 64) {
;             const int rr = e / 129, n = e % 129;
;             int bk = n;
;             if (n >= 16) bk = 16 + (n >= 19) + (n >= 21) + (n >= 24) + (n >= 27) + (n >= 31) + (n >= 35) + (n >= 40) + (n >= 46) + (n >= 52) + (n >= 59) + (n >= 67) + (n >= 77) + (n >= 87) + (n >= 99) + (n >= 113);
;             lut[rr * 132 + n] = relb[bk * 8 + g * 4 + rr] * LOG2E;
;         }
;     }
	v_sub_u32_e32 v3, 34, v6
	v_lshrrev_b32_e32 v7, 31, v7
	v_lshrrev_b32_e32 v3, 31, v3
	v_add3_u32 v5, v5, v7, v3
	v_sub_u32_e32 v7, 39, v6
	v_sub_u32_e32 v3, 45, v6
	v_lshrrev_b32_e32 v7, 31, v7
	v_lshrrev_b32_e32 v3, 31, v3
	v_add3_u32 v5, v5, v7, v3
	v_sub_u32_e32 v7, 51, v6
	v_sub_u32_e32 v3, 58, v6
	v_lshrrev_b32_e32 v7, 31, v7
	v_lshrrev_b32_e32 v3, 31, v3
	v_add3_u32 v5, v5, v7, v3
	v_sub_u32_e32 v7, 66, v6
	v_sub_u32_e32 v3, 76, v6
	v_lshrrev_b32_e32 v7, 31, v7
	v_lshrrev_b32_e32 v3, 31, v3
	v_add3_u32 v5, v5, v7, v3
	v_sub_u32_e32 v7, 86, v6
	v_sub_u32_e32 v3, 98, v6
	v_lshrrev_b32_e32 v7, 31, v7
	v_lshrrev_b32_e32 v3, 31, v3
	v_add3_u32 v5, v5, v7, v3
	v_sub_u32_e32 v7, 112, v6
	v_lshrrev_b32_e32 v7, 31, v7
	v_add_u32_e32 v5, v5, v7
	v_min_u32_e32 v5, v5, v6
	v_lshlrev_b32_e32 v3, 3, v5
	v_add3_u32 v235, v1, s3, v3
	v_lshlrev_b32_e32 v235, 2, v235
	v_add_u32_e32 v4, 256, v145
	v_mul_hi_i32 v1, v4, s2
	v_lshrrev_b32_e32 v3, 31, v1
	v_ashrrev_i32_e32 v1, 3, v1
	v_add_u32_e32 v1, v1, v3
	v_mul_u32_u24_e32 v3, 0x81, v1
	v_sub_u32_e32 v6, v4, v3
	v_mul_u32_u24_e32 v3, 12, v1
	v_add_u32_e32 v245, v2, v3
	v_mov_b32_e32 v5, 16
	v_sub_u32_e32 v7, 18, v6
	v_sub_u32_e32 v3, 20, v6
	v_lshrrev_b32_e32 v7, 31, v7
	v_lshrrev_b32_e32 v3, 31, v3
	v_add3_u32 v5, v5, v7, v3
	v_sub_u32_e32 v7, 23, v6
	v_sub_u32_e32 v3, 26, v6
	v_lshrrev_b32_e32 v7, 31, v7
	v_lshrrev_b32_e32 v3, 31, v3
	v_add3_u32 v5, v5, v7, v3
	v_sub_u32_e32 v7, 30, v6
	v_sub_u32_e32 v3, 34, v6
	v_lshrrev_b32_e32 v7, 31, v7
	v_lshrrev_b32_e32 v3, 31, v3
	v_add3_u32 v5, v5, v7, v3
	v_sub_u32_e32 v7, 39, v6
	v_sub_u32_e32 v3, 45, v6
	v_lshrrev_b32_e32 v7, 31, v7
	v_lshrrev_b32_e32 v3, 31, v3
	v_add3_u32 v5, v5, v7, v3
	v_sub_u32_e32 v7, 51, v6
	v_sub_u32_e32 v3, 58, v6
	v_lshrrev_b32_e32 v7, 31, v7
	v_lshrrev_b32_e32 v3, 31, v3
	v_add3_u32 v5, v5, v7, v3
	v_sub_u32_e32 v7, 66, v6
	v_sub_u32_e32 v3, 76, v6
	v_lshrrev_b32_e32 v7, 31, v7
	v_lshrrev_b32_e32 v3, 31, v3
	v_add3_u32 v5, v5, v7, v3
	v_sub_u32_e32 v7, 86, v6
	v_sub_u32_e32 v3, 98, v6
	v_lshrrev_b32_e32 v7, 31, v7
	v_lshrrev_b32_e32 v3, 31, v3
	v_add3_u32 v5, v5, v7, v3
	v_sub_u32_e32 v7, 112, v6
	v_lshrrev_b32_e32 v7, 31, v7
	v_add_u32_e32 v5, v5, v7
	v_min_u32_e32 v5, v5, v6
	v_lshlrev_b32_e32 v3, 3, v5
	v_add3_u32 v236, v1, s3, v3
	v_lshlrev_b32_e32 v236, 2, v236
	v_add_u32_e32 v4, 320, v145
	v_mul_hi_i32 v1, v4, s2
	v_lshrrev_b32_e32 v3, 31, v1
	v_ashrrev_i32_e32 v1, 3, v1
	v_add_u32_e32 v1, v1, v3
	v_mul_u32_u24_e32 v3, 0x81, v1
	v_sub_u32_e32 v6, v4, v3
	v_mul_u32_u24_e32 v3, 12, v1
	v_add_u32_e32 v246, v2, v3
	v_mov_b32_e32 v5, 16
	v_sub_u32_e32 v7, 18, v6
	v_sub_u32_e32 v3, 20, v6
	v_lshrrev_b32_e32 v7, 31, v7
	v_lshrrev_b32_e32 v3, 31, v3
	v_add3_u32 v5, v5, v7, v3
	v_sub_u32_e32 v7, 23, v6
	v_sub_u32_e32 v3, 26, v6
	v_lshrrev_b32_e32 v7, 31, v7
	v_lshrrev_b32_e32 v3, 31, v3
	v_add3_u32 v5, v5, v7, v3
	v_sub_u32_e32 v7, 30, v6
	v_sub_u32_e32 v3, 34, v6
	v_lshrrev_b32_e32 v7, 31, v7
	v_lshrrev_b32_e32 v3, 31, v3
	v_add3_u32 v5, v5, v7, v3
	v_sub_u32_e32 v7, 39, v6
	v_sub_u32_e32 v3, 45, v6
	v_lshrrev_b32_e32 v7, 31, v7
	v_lshrrev_b32_e32 v3, 31, v3
	v_add3_u32 v5, v5, v7, v3
	v_sub_u32_e32 v7, 51, v6
	v_sub_u32_e32 v3, 58, v6
	v_lshrrev_b32_e32 v7, 31, v7
	v_lshrrev_b32_e32 v3, 31, v3
	v_add3_u32 v5, v5, v7, v3
	v_sub_u32_e32 v7, 66, v6
	v_sub_u32_e32 v3, 76, v6
	v_lshrrev_b32_e32 v7, 31, v7
	v_lshrrev_b32_e32 v3, 31, v3
	v_add3_u32 v5, v5, v7, v3
	v_sub_u32_e32 v7, 86, v6
	v_sub_u32_e32 v3, 98, v6
	v_lshrrev_b32_e32 v7, 31, v7
	v_lshrrev_b32_e32 v3, 31, v3
	v_add3_u32 v5, v5, v7, v3
	v_sub_u32_e32 v7, 112, v6
	v_lshrrev_b32_e32 v7, 31, v7
	v_add_u32_e32 v5, v5, v7
	v_min_u32_e32 v5, v5, v6
	v_lshlrev_b32_e32 v3, 3, v5
	v_add3_u32 v237, v1, s3, v3
	v_lshlrev_b32_e32 v237, 2, v237
	v_add_u32_e32 v4, 384, v145
	v_mul_hi_i32 v1, v4, s2
	v_lshrrev_b32_e32 v3, 31, v1
	v_ashrrev_i32_e32 v1, 3, v1
	v_add_u32_e32 v1, v1, v3
	v_mul_u32_u24_e32 v3, 0x81, v1
	v_sub_u32_e32 v6, v4, v3
	v_mul_u32_u24_e32 v3, 12, v1
	v_add_u32_e32 v247, v2, v3
	v_mov_b32_e32 v5, 16
	v_sub_u32_e32 v7, 18, v6
	v_sub_u32_e32 v3, 20, v6
	v_lshrrev_b32_e32 v7, 31, v7
	v_lshrrev_b32_e32 v3, 31, v3
	v_add3_u32 v5, v5, v7, v3
	v_sub_u32_e32 v7, 23, v6
	v_sub_u32_e32 v3, 26, v6
	v_lshrrev_b32_e32 v7, 31, v7
	v_lshrrev_b32_e32 v3, 31, v3
	v_add3_u32 v5, v5, v7, v3
	v_sub_u32_e32 v7, 30, v6
	v_sub_u32_e32 v3, 34, v6
	v_lshrrev_b32_e32 v7, 31, v7
	v_lshrrev_b32_e32 v3, 31, v3
	v_add3_u32 v5, v5, v7, v3
	v_sub_u32_e32 v7, 39, v6
	v_sub_u32_e32 v3, 45, v6
	v_lshrrev_b32_e32 v7, 31, v7
	v_lshrrev_b32_e32 v3, 31, v3
	v_add3_u32 v5, v5, v7, v3
	v_sub_u32_e32 v7, 51, v6
	v_sub_u32_e32 v3, 58, v6
; __device__ __forceinline__ void nsa_unit(const Params& p, int bg, int jq, LAS unsigned char* lds, int wave, int lane, bool build_lut) {
;     ...
;     if (build_lut) {
;         for (int e = lane; e < 4 * 129; e += 64) {
;             const int rr = e / 129, n = e % 129;
;             int bk = n;
;             if (n >= 16) bk = 16 + (n >= 19) + (n >= 21) + (n >= 24) + (n >= 27) + (n >= 31) + (n >= 35) + (n >= 40) + (n >= 46) + (n >= 52) + (n >= 59) + (n >= 67) + (n >= 77) + (n >= 87) + (n >= 99) + (n >= 113);
;             lut[rr * 132 + n] = relb[bk * 8 + g * 4 + rr] * LOG2E;
;         }
;     }
	v_lshrrev_b32_e32 v7, 31, v7
	v_lshrrev_b32_e32 v3, 31, v3
	v_add3_u32 v5, v5, v7, v3
	v_sub_u32_e32 v7, 66, v6
	v_sub_u32_e32 v3, 76, v6
	v_lshrrev_b32_e32 v7, 31, v7
	v_lshrrev_b32_e32 v3, 31, v3
	v_add3_u32 v5, v5, v7, v3
	v_sub_u32_e32 v7, 86, v6
	v_sub_u32_e32 v3, 98, v6
	v_lshrrev_b32_e32 v7, 31, v7
	v_lshrrev_b32_e32 v3, 31, v3
	v_add3_u32 v5, v5, v7, v3
	v_sub_u32_e32 v7, 112, v6
	v_lshrrev_b32_e32 v7, 31, v7
	v_add_u32_e32 v5, v5, v7
	v_min_u32_e32 v5, v5, v6
	v_lshlrev_b32_e32 v3, 3, v5
	v_add3_u32 v238, v1, s3, v3
	v_lshlrev_b32_e32 v238, 2, v238
	v_add_u32_e32 v4, 448, v145
	v_mul_hi_i32 v1, v4, s2
	v_lshrrev_b32_e32 v3, 31, v1
	v_ashrrev_i32_e32 v1, 3, v1
	v_add_u32_e32 v1, v1, v3
	v_mul_u32_u24_e32 v3, 0x81, v1
	v_sub_u32_e32 v6, v4, v3
	v_mul_u32_u24_e32 v3, 12, v1
	v_add_u32_e32 v248, v2, v3
	v_mov_b32_e32 v5, 16
	v_sub_u32_e32 v7, 18, v6
	v_sub_u32_e32 v3, 20, v6
	v_lshrrev_b32_e32 v7, 31, v7
	v_lshrrev_b32_e32 v3, 31, v3
	v_add3_u32 v5, v5, v7, v3
	v_sub_u32_e32 v7, 23, v6
	v_sub_u32_e32 v3, 26, v6
	v_lshrrev_b32_e32 v7, 31, v7
	v_lshrrev_b32_e32 v3, 31, v3
	v_add3_u32 v5, v5, v7, v3
	v_sub_u32_e32 v7, 30, v6
	v_sub_u32_e32 v3, 34, v6
	v_lshrrev_b32_e32 v7, 31, v7
	v_lshrrev_b32_e32 v3, 31, v3
	v_add3_u32 v5, v5, v7, v3
	v_sub_u32_e32 v7, 39, v6
	v_sub_u32_e32 v3, 45, v6
	v_lshrrev_b32_e32 v7, 31, v7
	v_lshrrev_b32_e32 v3, 31, v3
	v_add3_u32 v5, v5, v7, v3
	v_sub_u32_e32 v7, 51, v6
	v_sub_u32_e32 v3, 58, v6
	v_lshrrev_b32_e32 v7, 31, v7
	v_lshrrev_b32_e32 v3, 31, v3
	v_add3_u32 v5, v5, v7, v3
	v_sub_u32_e32 v7, 66, v6
	v_sub_u32_e32 v3, 76, v6
	v_lshrrev_b32_e32 v7, 31, v7
	v_lshrrev_b32_e32 v3, 31, v3
	v_add3_u32 v5, v5, v7, v3
	v_sub_u32_e32 v7, 86, v6
	v_sub_u32_e32 v3, 98, v6
	v_lshrrev_b32_e32 v7, 31, v7
	v_lshrrev_b32_e32 v3, 31, v3
	v_add3_u32 v5, v5, v7, v3
	v_sub_u32_e32 v7, 112, v6
	v_lshrrev_b32_e32 v7, 31, v7
	v_add_u32_e32 v5, v5, v7
	v_min_u32_e32 v5, v5, v6
	v_lshlrev_b32_e32 v3, 3, v5
	v_add3_u32 v239, v1, s3, v3
	v_lshlrev_b32_e32 v239, 2, v239
	v_add_u32_e32 v4, 512, v145
	v_mul_hi_i32 v1, v4, s2
	v_lshrrev_b32_e32 v3, 31, v1
	v_ashrrev_i32_e32 v1, 3, v1
	v_add_u32_e32 v1, v1, v3
	v_mul_u32_u24_e32 v3, 0x81, v1
	v_sub_u32_e32 v6, v4, v3
	v_mul_u32_u24_e32 v3, 12, v1
	v_add_u32_e32 v249, v2, v3
	v_mov_b32_e32 v5, 16
	v_sub_u32_e32 v7, 18, v6
	v_sub_u32_e32 v3, 20, v6
	v_lshrrev_b32_e32 v7, 31, v7
	v_lshrrev_b32_e32 v3, 31, v3
	v_add3_u32 v5, v5, v7, v3
	v_sub_u32_e32 v7, 23, v6
	v_sub_u32_e32 v3, 26, v6
	v_lshrrev_b32_e32 v7, 31, v7
	v_lshrrev_b32_e32 v3, 31, v3
	v_add3_u32 v5, v5, v7, v3
	v_sub_u32_e32 v7, 30, v6
	v_sub_u32_e32 v3, 34, v6
	v_lshrrev_b32_e32 v7, 31, v7
	v_lshrrev_b32_e32 v3, 31, v3
	v_add3_u32 v5, v5, v7, v3
	v_sub_u32_e32 v7, 39, v6
	v_sub_u32_e32 v3, 45, v6
	v_lshrrev_b32_e32 v7, 31, v7
	v_lshrrev_b32_e32 v3, 31, v3
	v_add3_u32 v5, v5, v7, v3
	v_sub_u32_e32 v7, 51, v6
	v_sub_u32_e32 v3, 58, v6
	v_lshrrev_b32_e32 v7, 31, v7
	v_lshrrev_b32_e32 v3, 31, v3
	v_add3_u32 v5, v5, v7, v3
	v_sub_u32_e32 v7, 66, v6
	v_sub_u32_e32 v3, 76, v6
	v_lshrrev_b32_e32 v7, 31, v7
	v_lshrrev_b32_e32 v3, 31, v3
	v_add3_u32 v5, v5, v7, v3
	v_sub_u32_e32 v7, 86, v6
	v_sub_u32_e32 v3, 98, v6
	v_lshrrev_b32_e32 v7, 31, v7
	v_lshrrev_b32_e32 v3, 31, v3
	v_add3_u32 v5, v5, v7, v3
	v_sub_u32_e32 v7, 112, v6
	v_lshrrev_b32_e32 v7, 31, v7
	v_add_u32_e32 v5, v5, v7
	v_min_u32_e32 v5, v5, v6
	v_lshlrev_b32_e32 v3, 3, v5
	v_add3_u32 v240, v1, s3, v3
	v_lshlrev_b32_e32 v240, 2, v240
	s_waitcnt lgkmcnt(0)
	global_load_dword v232, v232, s[6:7]
	global_load_dword v233, v233, s[6:7]
	global_load_dword v234, v234, s[6:7]
	global_load_dword v235, v235, s[6:7]
	global_load_dword v236, v236, s[6:7]
	global_load_dword v237, v237, s[6:7]
	global_load_dword v238, v238, s[6:7]
	global_load_dword v239, v239, s[6:7]
	v_cmp_gt_u32_e32 vcc, 4, v145
	s_and_saveexec_b64 s[10:11], vcc
	global_load_dword v240, v240, s[6:7]
	s_or_b64 exec, exec, s[10:11]
	s_waitcnt vmcnt(0)
	v_mul_f32_e32 v232, 0x3fb8aa3b, v232
	ds_write_b32 v241, v232
	v_mul_f32_e32 v233, 0x3fb8aa3b, v233
	ds_write_b32 v242, v233 offset:256
	v_mul_f32_e32 v234, 0x3fb8aa3b, v234
	ds_write_b32 v243, v234 offset:512
	v_mul_f32_e32 v235, 0x3fb8aa3b, v235
	ds_write_b32 v244, v235 offset:768
	v_mul_f32_e32 v236, 0x3fb8aa3b, v236
	ds_write_b32 v245, v236 offset:1024
	v_mul_f32_e32 v237, 0x3fb8aa3b, v237
	ds_write_b32 v246, v237 offset:1280
	v_mul_f32_e32 v238, 0x3fb8aa3b, v238
	ds_write_b32 v247, v238 offset:1536
	v_mul_f32_e32 v239, 0x3fb8aa3b, v239
	ds_write_b32 v248, v239 offset:1792
	s_and_b64 exec, exec, vcc
	v_mul_f32_e32 v240, 0x3fb8aa3b, v240
	ds_write_b32 v249, v240 offset:2048
